# v006 + attention near/far loops: reuse the V-DMA pair base offsets for the K loads instead of recomputing them (scalar CSE)
# speedup vs baseline: 1.0051x; 1.0051x over previous
; __device__ __forceinline__ void attn_pair_bases(int pi, int r4, int j0, int rowbase, int h, unsigned& ua, unsigned& ub) {
;     int rk, jtA; bool same; pair_decode(pi, r4, j0, rk, jtA, same);
;     const int jtB = jtA + 16;
;     const bool vA = (jtA >= 0) && (jtA < 2048), vB = (jtB >= 0) && (jtB < 2048);
;     const int jA = vA ? jtA : jtB, jB = vB ? jtB : jtA;
;     ua = (unsigned)(((rowbase + 4 * jA + rk) * AW + h * 64) * 2); ub = (unsigned)(((rowbase + 4 * jB + rk) * AW + h * 64) * 2);
; }
; __device__ __forceinline__ void attn_load_k(int pi, int r4, int j0, int rowbase, int h, int klo, __amdgpu_buffer_rsrc_t Kr, bf16x8 (&Kn)[4]) {
;     unsigned ua, ub; attn_pair_bases(pi, r4, j0, rowbase, h, ua, ub);
;     Kn[0] = __builtin_bit_cast(bf16x8, __builtin_amdgcn_raw_buffer_load_b128(Kr, klo, ua, 0)); Kn[1] = __builtin_bit_cast(bf16x8, __builtin_amdgcn_raw_buffer_load_b128(Kr, klo + 64, ua, 0));
;     Kn[2] = __builtin_bit_cast(bf16x8, __builtin_amdgcn_raw_buffer_load_b128(Kr, klo, ub, 0)); Kn[3] = __builtin_bit_cast(bf16x8, __builtin_amdgcn_raw_buffer_load_b128(Kr, klo + 64, ub, 0));
; template <int MODE, int DRY, int QLO, int QHI>
; __device__ __forceinline__ int attn_step(int o, int& par, const AttnCtx& C, const AttnLane& L, f32x4 (&O)[4][4], float (&mrun)[4], float (&lrun)[4], const bf16x8 (&Qf)[4][2], bf16x8 (&Kn)[4]) {
;     ...
;         sA[qt] = __builtin_amdgcn_mfma_f32_16x16x32_bf16(Kn[0], Qf[qt][0], (f32x4){0.f, 0.f, 0.f, 0.f}, 0, 0, 0); sA[qt] = __builtin_amdgcn_mfma_f32_16x16x32_bf16(Kn[1], Qf[qt][1], sA[qt], 0, 0, 0);
;         sB[qt] = __builtin_amdgcn_mfma_f32_16x16x32_bf16(Kn[2], Qf[qt][0], (f32x4){0.f, 0.f, 0.f, 0.f}, 0, 0, 0); sB[qt] = __builtin_amdgcn_mfma_f32_16x16x32_bf16(Kn[3], Qf[qt][1], sB[qt], 0, 0, 0);
;     }
;     if (DRY != 2) if (on < 27) attn_load_k(pn, C.r4, C.j0, C.rowbase, C.h, C.klo, C.Kr, Kn);
.LBB0_582:
	v_mfma_f32_16x16x32_bf16 v[128:131], v[100:103], v[64:67], 0
	s_and_b64 vcc, exec, s[0:1]
	v_mfma_f32_16x16x32_bf16 v[156:159], v[108:111], v[68:71], v[128:131]
	v_mfma_f32_16x16x32_bf16 v[128:131], v[96:99], v[64:67], 0
	v_mfma_f32_16x16x32_bf16 v[152:155], v[104:107], v[68:71], v[128:131]
	v_mfma_f32_16x16x32_bf16 v[128:131], v[100:103], v[72:75], 0
	v_mfma_f32_16x16x32_bf16 v[148:151], v[108:111], v[76:79], v[128:131]
	v_mfma_f32_16x16x32_bf16 v[128:131], v[96:99], v[72:75], 0
	v_mfma_f32_16x16x32_bf16 v[144:147], v[104:107], v[76:79], v[128:131]
	v_mfma_f32_16x16x32_bf16 v[128:131], v[100:103], v[80:83], 0
	v_mfma_f32_16x16x32_bf16 v[140:143], v[108:111], v[84:87], v[128:131]
	v_mfma_f32_16x16x32_bf16 v[128:131], v[96:99], v[80:83], 0
	v_mfma_f32_16x16x32_bf16 v[136:139], v[104:107], v[84:87], v[128:131]
	v_mfma_f32_16x16x32_bf16 v[128:131], v[100:103], v[88:91], 0
	v_mfma_f32_16x16x32_bf16 v[132:135], v[96:99], v[88:91], 0
	v_mfma_f32_16x16x32_bf16 v[128:131], v[108:111], v[92:95], v[128:131]
	v_mfma_f32_16x16x32_bf16 v[132:135], v[104:107], v[92:95], v[132:135]
	s_cbranch_vccnz .LBB0_587
	s_mov_b32 s42, s10
	s_mov_b32 s43, s11
	buffer_load_dwordx4 v[100:103], v184, s[40:43], s14 offen
	buffer_load_dwordx4 v[96:99], v184, s[40:43], s4 offen
	buffer_load_dwordx4 v[108:111], v185, s[40:43], s14 offen
	buffer_load_dwordx4 v[104:107], v185, s[40:43], s4 offen
